# P9 final norm: 8 rows per wave loaded up front, gain vector loaded once, counted waits
# speedup vs baseline: 1.0047x; 1.0047x over previous
; __device__ __forceinline__ void unpack8(u32x4 r, float* f) { f[0] = bflo(r.x); f[1] = bfhi(r.x); f[2] = bflo(r.y); f[3] = bfhi(r.y); f[4] = bflo(r.z); f[5] = bfhi(r.z); f[6] = bflo(r.w); f[7] = bfhi(r.w); }
;     __device__ __forceinline__ PT() { out = (float*)(__attribute__((address_space(1))) float*)ptab_get(23); ws = (unsigned char*)(__attribute__((address_space(1))) unsigned char*)ptab_get(24); }
; __device__ __forceinline__ void phase_final(const PT& p, int lane, int wave) {
;     const float* st2 = (const float*)(p.ws + WS_ST2); const float* g = p.in[22]; const bf16* X2 = (const bf16*)(p.ws + WS_X2B);
;     for (int m = blockIdx.x * 8 + wave; m < M; m += gridDim.x * 8) {
;         const float rs = rsqrtf(st2[m] * (1.f / 2048.f) + EPS);
;         const u32x4* xr = (const u32x4*)(X2 + (size_t)m * 2048) + lane; f32x4* orow = (f32x4*)(p.out + (size_t)m * 2048);
; #pragma unroll
;         for (int j = 0; j < 4; ++j) {
;             float f[8]; unpack8(xr[64 * j], f); const int c = 8 * (lane + 64 * j);
;             const f32x4 g0 = *(const f32x4*)(g + c), g1 = *(const f32x4*)(g + c + 4);
;             orow[(c >> 2)] = (f32x4){f[0] * rs * g0.x, f[1] * rs * g0.y, f[2] * rs * g0.z, f[3] * rs * g0.w};
;             orow[(c >> 2) + 1] = (f32x4){f[4] * rs * g1.x, f[5] * rs * g1.y, f[6] * rs * g1.z, f[7] * rs * g1.w};
;         }
;     }
.LBB0_1257:
	s_or_b64 exec, exec, s[0:1]
	s_waitcnt lgkmcnt(0)
	v_mov_b32_e32 v0, 0x23eb8
	s_barrier
	ds_read_b64 v[0:1], v0
	v_mov_b32_e32 v2, 0x23ec0
	ds_read_b64 v[2:3], v2
	v_readlane_b32 s1, v249, 2
	s_waitcnt lgkmcnt(1)
	v_readfirstlane_b32 s7, v0
	v_mov_b32_e32 v0, 0x23eb0
	v_readfirstlane_b32 s6, v1
	ds_read_b64 v[0:1], v0
	v_readfirstlane_b32 s0, v196
	s_ashr_i32 s0, s0, 6
	s_add_i32 s0, s0, s1
	s_waitcnt lgkmcnt(1)
	v_readfirstlane_b32 s5, v3
	v_readfirstlane_b32 s4, v2
	s_waitcnt lgkmcnt(0)
	v_readfirstlane_b32 s3, v1
	s_cmpk_gt_i32 s0, 0x3fff
	v_readfirstlane_b32 s2, v0
	s_cbranch_scc1 .LBB0_1260
	v_and_b32_e32 v10, 63, v196
	v_lshlrev_b32_e32 v0, 4, v10
	v_mov_b32_e32 v1, 0
	v_lshl_add_u64 v[2:3], s[4:5], 0, v[0:1]
	v_lshlrev_b32_e32 v0, 5, v10
	v_or_b32_e32 v8, 64, v10
	v_lshl_add_u64 v[4:5], s[2:3], 0, v[0:1]
	v_lshlrev_b32_e32 v0, 5, v8
	v_or_b32_e32 v11, 0x80, v10
	s_add_u32 s8, s4, 0x30000
	v_lshl_add_u64 v[6:7], s[2:3], 0, v[0:1]
	v_lshlrev_b32_e32 v0, 5, v11
	v_or_b32_e32 v13, 0xc0, v10
	s_addc_u32 s9, s5, 0
	s_mov_b64 s[4:5], 0x6900000
	v_lshlrev_b32_e32 v12, 1, v10
	v_lshlrev_b32_e32 v14, 1, v8
	v_lshl_add_u64 v[8:9], s[2:3], 0, v[0:1]
	v_lshlrev_b32_e32 v16, 1, v11
	v_lshlrev_b32_e32 v0, 5, v13
	v_lshlrev_b32_e32 v18, 1, v13
	v_lshl_add_u64 v[2:3], v[2:3], 0, s[4:5]
	v_lshl_add_u64 v[10:11], s[2:3], 0, v[0:1]
	v_mov_b32_e32 v0, 0x3727c5ac
	s_mov_b32 s4, 0x800000
	v_lshlrev_b32_e32 v12, 4, v12
	v_lshlrev_b32_e32 v13, 4, v14
	v_lshlrev_b32_e32 v14, 4, v16
	v_lshlrev_b32_e32 v15, 4, v18
	s_mov_b32 s14, s0
	global_load_dwordx4 v[16:19], v[4:5], off
	global_load_dwordx4 v[20:23], v[4:5], off offset:16
	global_load_dwordx4 v[24:27], v[6:7], off
	global_load_dwordx4 v[28:31], v[6:7], off offset:16
	global_load_dwordx4 v[32:35], v[8:9], off
	global_load_dwordx4 v[36:39], v[8:9], off offset:16
	global_load_dwordx4 v[40:43], v[10:11], off
	global_load_dwordx4 v[44:47], v[10:11], off offset:16
	s_ashr_i32 s1, s0, 31
	s_lshl_b64 s[12:13], s[0:1], 2
	s_add_u32 s12, s8, s12
	s_addc_u32 s13, s9, s13
	global_load_dword v48, v1, s[12:13]
	s_lshl_b64 s[12:13], s[0:1], 12
	v_lshl_add_u64 v[216:217], v[2:3], 0, s[12:13]
	global_load_dwordx4 v[64:67], v[216:217], off
	global_load_dwordx4 v[68:71], v[216:217], off offset:1024
	global_load_dwordx4 v[72:75], v[216:217], off offset:2048
	global_load_dwordx4 v[76:79], v[216:217], off offset:3072
	s_add_i32 s0, s0, s80
	s_ashr_i32 s1, s0, 31
	s_lshl_b64 s[12:13], s[0:1], 2
	s_add_u32 s12, s8, s12
	s_addc_u32 s13, s9, s13
	global_load_dword v49, v1, s[12:13]
	s_lshl_b64 s[12:13], s[0:1], 12
	v_lshl_add_u64 v[220:221], v[2:3], 0, s[12:13]
	global_load_dwordx4 v[80:83], v[220:221], off
	global_load_dwordx4 v[84:87], v[220:221], off offset:1024
	global_load_dwordx4 v[88:91], v[220:221], off offset:2048
	global_load_dwordx4 v[92:95], v[220:221], off offset:3072
	s_add_i32 s0, s0, s80
	s_ashr_i32 s1, s0, 31
	s_lshl_b64 s[12:13], s[0:1], 2
	s_add_u32 s12, s8, s12
	s_addc_u32 s13, s9, s13
	global_load_dword v50, v1, s[12:13]
	s_lshl_b64 s[12:13], s[0:1], 12
	v_lshl_add_u64 v[216:217], v[2:3], 0, s[12:13]
	global_load_dwordx4 v[96:99], v[216:217], off
	global_load_dwordx4 v[100:103], v[216:217], off offset:1024
	global_load_dwordx4 v[104:107], v[216:217], off offset:2048
	global_load_dwordx4 v[108:111], v[216:217], off offset:3072
	s_add_i32 s0, s0, s80
	s_ashr_i32 s1, s0, 31
	s_lshl_b64 s[12:13], s[0:1], 2
	s_add_u32 s12, s8, s12
	s_addc_u32 s13, s9, s13
	global_load_dword v51, v1, s[12:13]
	s_lshl_b64 s[12:13], s[0:1], 12
	v_lshl_add_u64 v[220:221], v[2:3], 0, s[12:13]
	global_load_dwordx4 v[112:115], v[220:221], off
	global_load_dwordx4 v[116:119], v[220:221], off offset:1024
	global_load_dwordx4 v[120:123], v[220:221], off offset:2048
	global_load_dwordx4 v[124:127], v[220:221], off offset:3072
	s_add_i32 s0, s0, s80
	s_ashr_i32 s1, s0, 31
	s_lshl_b64 s[12:13], s[0:1], 2
	s_add_u32 s12, s8, s12
	s_addc_u32 s13, s9, s13
	global_load_dword v52, v1, s[12:13]
	s_lshl_b64 s[12:13], s[0:1], 12
	v_lshl_add_u64 v[216:217], v[2:3], 0, s[12:13]
	global_load_dwordx4 v[128:131], v[216:217], off
	global_load_dwordx4 v[132:135], v[216:217], off offset:1024
	global_load_dwordx4 v[136:139], v[216:217], off offset:2048
	global_load_dwordx4 v[140:143], v[216:217], off offset:3072
	s_add_i32 s0, s0, s80
	s_ashr_i32 s1, s0, 31
	s_lshl_b64 s[12:13], s[0:1], 2
	s_add_u32 s12, s8, s12
	s_addc_u32 s13, s9, s13
	global_load_dword v53, v1, s[12:13]
	s_lshl_b64 s[12:13], s[0:1], 12
	v_lshl_add_u64 v[220:221], v[2:3], 0, s[12:13]
	global_load_dwordx4 v[144:147], v[220:221], off
	global_load_dwordx4 v[148:151], v[220:221], off offset:1024
	global_load_dwordx4 v[152:155], v[220:221], off offset:2048
	global_load_dwordx4 v[156:159], v[220:221], off offset:3072
	s_add_i32 s0, s0, s80
	s_ashr_i32 s1, s0, 31
	s_lshl_b64 s[12:13], s[0:1], 2
	s_add_u32 s12, s8, s12
	s_addc_u32 s13, s9, s13
	global_load_dword v54, v1, s[12:13]
	s_lshl_b64 s[12:13], s[0:1], 12
	v_lshl_add_u64 v[216:217], v[2:3], 0, s[12:13]
	global_load_dwordx4 v[160:163], v[216:217], off
	global_load_dwordx4 v[164:167], v[216:217], off offset:1024
	global_load_dwordx4 v[168:171], v[216:217], off offset:2048
	global_load_dwordx4 v[172:175], v[216:217], off offset:3072
	s_add_i32 s0, s0, s80
	s_ashr_i32 s1, s0, 31
	s_lshl_b64 s[12:13], s[0:1], 2
	s_add_u32 s12, s8, s12
	s_addc_u32 s13, s9, s13
	global_load_dword v55, v1, s[12:13]
	s_lshl_b64 s[12:13], s[0:1], 12
	v_lshl_add_u64 v[220:221], v[2:3], 0, s[12:13]
	global_load_dwordx4 v[176:179], v[220:221], off
	global_load_dwordx4 v[180:183], v[220:221], off offset:1024
	global_load_dwordx4 v[184:187], v[220:221], off offset:2048
	global_load_dwordx4 v[188:191], v[220:221], off offset:3072
	s_add_i32 s0, s0, s80
	s_mov_b32 s0, s14
	s_ashr_i32 s1, s0, 31
	s_lshl_b64 s[2:3], s[0:1], 13
	s_add_u32 s2, s7, s2
	s_addc_u32 s3, s6, s3
	s_add_i32 s0, s0, s80
	s_waitcnt vmcnt(39)
; __device__ __forceinline__ void unpack8(u32x4 r, float* f) { f[0] = bflo(r.x); f[1] = bfhi(r.x); f[2] = bflo(r.y); f[3] = bfhi(r.y); f[4] = bflo(r.z); f[5] = bfhi(r.z); f[6] = bflo(r.w); f[7] = bfhi(r.w); }
; __device__ __forceinline__ void phase_final(const PT& p, int lane, int wave) {
;     ...
;         const float rs = rsqrtf(st2[m] * (1.f / 2048.f) + EPS);
;         const u32x4* xr = (const u32x4*)(X2 + (size_t)m * 2048) + lane; f32x4* orow = (f32x4*)(p.out + (size_t)m * 2048);
; #pragma unroll
;         for (int j = 0; j < 4; ++j) {
;             float f[8]; unpack8(xr[64 * j], f); const int c = 8 * (lane + 64 * j);
;             const f32x4 g0 = *(const f32x4*)(g + c), g1 = *(const f32x4*)(g + c + 4);
;             orow[(c >> 2)] = (f32x4){f[0] * rs * g0.x, f[1] * rs * g0.y, f[2] * rs * g0.z, f[3] * rs * g0.w};
;             orow[(c >> 2) + 1] = (f32x4){f[4] * rs * g1.x, f[5] * rs * g1.y, f[6] * rs * g1.z, f[7] * rs * g1.w};
	v_fmamk_f32 v220, v48, 0x3a000000, v0
	v_mul_f32_e32 v221, 0x4b800000, v220
	v_cmp_gt_f32_e32 vcc, s4, v220
	s_nop 1
	v_cndmask_b32_e32 v220, v220, v221, vcc
	v_rsq_f32_e32 v218, v220
	s_nop 0
	v_mul_f32_e32 v221, 0x45800000, v218
	v_cndmask_b32_e32 v218, v218, v221, vcc
	s_waitcnt vmcnt(38)
	v_lshlrev_b32_e32 v200, 16, v64
	v_and_b32_e32 v201, 0xffff0000, v64
	v_lshlrev_b32_e32 v202, 16, v65
	v_and_b32_e32 v203, 0xffff0000, v65
	v_lshlrev_b32_e32 v204, 16, v66
	v_and_b32_e32 v205, 0xffff0000, v66
	v_lshlrev_b32_e32 v206, 16, v67
	v_and_b32_e32 v207, 0xffff0000, v67
	v_pk_mul_f32 v[200:201], v[218:219], v[200:201] op_sel_hi:[0,1]
	v_pk_mul_f32 v[202:203], v[218:219], v[202:203] op_sel_hi:[0,1]
	v_pk_mul_f32 v[204:205], v[218:219], v[204:205] op_sel_hi:[0,1]
	v_pk_mul_f32 v[206:207], v[218:219], v[206:207] op_sel_hi:[0,1]
	v_pk_mul_f32 v[208:209], v[16:17], v[200:201]
	v_pk_mul_f32 v[210:211], v[18:19], v[202:203]
	v_pk_mul_f32 v[212:213], v[20:21], v[204:205]
	v_pk_mul_f32 v[214:215], v[22:23], v[206:207]
	global_store_dwordx4 v12, v[208:211], s[2:3]
	global_store_dwordx4 v12, v[212:215], s[2:3] offset:16
	s_waitcnt vmcnt(39)
	v_lshlrev_b32_e32 v200, 16, v68
	v_and_b32_e32 v201, 0xffff0000, v68
	v_lshlrev_b32_e32 v202, 16, v69
	v_and_b32_e32 v203, 0xffff0000, v69
	v_lshlrev_b32_e32 v204, 16, v70
	v_and_b32_e32 v205, 0xffff0000, v70
	v_lshlrev_b32_e32 v206, 16, v71
	v_and_b32_e32 v207, 0xffff0000, v71
	v_pk_mul_f32 v[200:201], v[218:219], v[200:201] op_sel_hi:[0,1]
	v_pk_mul_f32 v[202:203], v[218:219], v[202:203] op_sel_hi:[0,1]
	v_pk_mul_f32 v[204:205], v[218:219], v[204:205] op_sel_hi:[0,1]
	v_pk_mul_f32 v[206:207], v[218:219], v[206:207] op_sel_hi:[0,1]
	v_pk_mul_f32 v[224:225], v[24:25], v[200:201]
	v_pk_mul_f32 v[226:227], v[26:27], v[202:203]
	v_pk_mul_f32 v[228:229], v[28:29], v[204:205]
	v_pk_mul_f32 v[230:231], v[30:31], v[206:207]
	global_store_dwordx4 v13, v[224:227], s[2:3]
	global_store_dwordx4 v13, v[228:231], s[2:3] offset:16
	s_waitcnt vmcnt(40)
	v_lshlrev_b32_e32 v200, 16, v72
	v_and_b32_e32 v201, 0xffff0000, v72
	v_lshlrev_b32_e32 v202, 16, v73
	v_and_b32_e32 v203, 0xffff0000, v73
	v_lshlrev_b32_e32 v204, 16, v74
	v_and_b32_e32 v205, 0xffff0000, v74
	v_lshlrev_b32_e32 v206, 16, v75
	v_and_b32_e32 v207, 0xffff0000, v75
	v_pk_mul_f32 v[200:201], v[218:219], v[200:201] op_sel_hi:[0,1]
	v_pk_mul_f32 v[202:203], v[218:219], v[202:203] op_sel_hi:[0,1]
	v_pk_mul_f32 v[204:205], v[218:219], v[204:205] op_sel_hi:[0,1]
	v_pk_mul_f32 v[206:207], v[218:219], v[206:207] op_sel_hi:[0,1]
	v_pk_mul_f32 v[208:209], v[32:33], v[200:201]
	v_pk_mul_f32 v[210:211], v[34:35], v[202:203]
	v_pk_mul_f32 v[212:213], v[36:37], v[204:205]
	v_pk_mul_f32 v[214:215], v[38:39], v[206:207]
	global_store_dwordx4 v14, v[208:211], s[2:3]
	global_store_dwordx4 v14, v[212:215], s[2:3] offset:16
	s_waitcnt vmcnt(41)
	v_lshlrev_b32_e32 v200, 16, v76
	v_and_b32_e32 v201, 0xffff0000, v76
	v_lshlrev_b32_e32 v202, 16, v77
	v_and_b32_e32 v203, 0xffff0000, v77
	v_lshlrev_b32_e32 v204, 16, v78
	v_and_b32_e32 v205, 0xffff0000, v78
	v_lshlrev_b32_e32 v206, 16, v79
	v_and_b32_e32 v207, 0xffff0000, v79
	v_pk_mul_f32 v[200:201], v[218:219], v[200:201] op_sel_hi:[0,1]
	v_pk_mul_f32 v[202:203], v[218:219], v[202:203] op_sel_hi:[0,1]
	v_pk_mul_f32 v[204:205], v[218:219], v[204:205] op_sel_hi:[0,1]
	v_pk_mul_f32 v[206:207], v[218:219], v[206:207] op_sel_hi:[0,1]
	v_pk_mul_f32 v[224:225], v[40:41], v[200:201]
	v_pk_mul_f32 v[226:227], v[42:43], v[202:203]
	v_pk_mul_f32 v[228:229], v[44:45], v[204:205]
	v_pk_mul_f32 v[230:231], v[46:47], v[206:207]
	global_store_dwordx4 v15, v[224:227], s[2:3]
	global_store_dwordx4 v15, v[228:231], s[2:3] offset:16
	s_ashr_i32 s1, s0, 31
	s_lshl_b64 s[2:3], s[0:1], 13
	s_add_u32 s2, s7, s2
	s_addc_u32 s3, s6, s3
	s_add_i32 s0, s0, s80
	s_waitcnt vmcnt(42)
	v_fmamk_f32 v220, v49, 0x3a000000, v0
	v_mul_f32_e32 v221, 0x4b800000, v220
	v_cmp_gt_f32_e32 vcc, s4, v220
	s_nop 1
	v_cndmask_b32_e32 v220, v220, v221, vcc
	v_rsq_f32_e32 v218, v220
	s_nop 0
	v_mul_f32_e32 v221, 0x45800000, v218
	v_cndmask_b32_e32 v218, v218, v221, vcc
	s_waitcnt vmcnt(41)
	v_lshlrev_b32_e32 v200, 16, v80
	v_and_b32_e32 v201, 0xffff0000, v80
	v_lshlrev_b32_e32 v202, 16, v81
	v_and_b32_e32 v203, 0xffff0000, v81
	v_lshlrev_b32_e32 v204, 16, v82
	v_and_b32_e32 v205, 0xffff0000, v82
	v_lshlrev_b32_e32 v206, 16, v83
	v_and_b32_e32 v207, 0xffff0000, v83
	v_pk_mul_f32 v[200:201], v[218:219], v[200:201] op_sel_hi:[0,1]
	v_pk_mul_f32 v[202:203], v[218:219], v[202:203] op_sel_hi:[0,1]
	v_pk_mul_f32 v[204:205], v[218:219], v[204:205] op_sel_hi:[0,1]
	v_pk_mul_f32 v[206:207], v[218:219], v[206:207] op_sel_hi:[0,1]
	v_pk_mul_f32 v[208:209], v[16:17], v[200:201]
	v_pk_mul_f32 v[210:211], v[18:19], v[202:203]
	v_pk_mul_f32 v[212:213], v[20:21], v[204:205]
	v_pk_mul_f32 v[214:215], v[22:23], v[206:207]
	global_store_dwordx4 v12, v[208:211], s[2:3]
	global_store_dwordx4 v12, v[212:215], s[2:3] offset:16
	s_waitcnt vmcnt(42)
	v_lshlrev_b32_e32 v200, 16, v84
	v_and_b32_e32 v201, 0xffff0000, v84
	v_lshlrev_b32_e32 v202, 16, v85
	v_and_b32_e32 v203, 0xffff0000, v85
	v_lshlrev_b32_e32 v204, 16, v86
	v_and_b32_e32 v205, 0xffff0000, v86
	v_lshlrev_b32_e32 v206, 16, v87
	v_and_b32_e32 v207, 0xffff0000, v87
	v_pk_mul_f32 v[200:201], v[218:219], v[200:201] op_sel_hi:[0,1]
	v_pk_mul_f32 v[202:203], v[218:219], v[202:203] op_sel_hi:[0,1]
	v_pk_mul_f32 v[204:205], v[218:219], v[204:205] op_sel_hi:[0,1]
	v_pk_mul_f32 v[206:207], v[218:219], v[206:207] op_sel_hi:[0,1]
	v_pk_mul_f32 v[224:225], v[24:25], v[200:201]
	v_pk_mul_f32 v[226:227], v[26:27], v[202:203]
	v_pk_mul_f32 v[228:229], v[28:29], v[204:205]
	v_pk_mul_f32 v[230:231], v[30:31], v[206:207]
	global_store_dwordx4 v13, v[224:227], s[2:3]
	global_store_dwordx4 v13, v[228:231], s[2:3] offset:16
	s_waitcnt vmcnt(43)
; __device__ __forceinline__ void unpack8(u32x4 r, float* f) { f[0] = bflo(r.x); f[1] = bfhi(r.x); f[2] = bflo(r.y); f[3] = bfhi(r.y); f[4] = bflo(r.z); f[5] = bfhi(r.z); f[6] = bflo(r.w); f[7] = bfhi(r.w); }
; __device__ __forceinline__ void phase_final(const PT& p, int lane, int wave) {
;     ...
;         const float rs = rsqrtf(st2[m] * (1.f / 2048.f) + EPS);
;         const u32x4* xr = (const u32x4*)(X2 + (size_t)m * 2048) + lane; f32x4* orow = (f32x4*)(p.out + (size_t)m * 2048);
; #pragma unroll
;         for (int j = 0; j < 4; ++j) {
;             float f[8]; unpack8(xr[64 * j], f); const int c = 8 * (lane + 64 * j);
;             const f32x4 g0 = *(const f32x4*)(g + c), g1 = *(const f32x4*)(g + c + 4);
;             orow[(c >> 2)] = (f32x4){f[0] * rs * g0.x, f[1] * rs * g0.y, f[2] * rs * g0.z, f[3] * rs * g0.w};
;             orow[(c >> 2) + 1] = (f32x4){f[4] * rs * g1.x, f[5] * rs * g1.y, f[6] * rs * g1.z, f[7] * rs * g1.w};
	v_lshlrev_b32_e32 v200, 16, v88
	v_and_b32_e32 v201, 0xffff0000, v88
	v_lshlrev_b32_e32 v202, 16, v89
	v_and_b32_e32 v203, 0xffff0000, v89
	v_lshlrev_b32_e32 v204, 16, v90
	v_and_b32_e32 v205, 0xffff0000, v90
	v_lshlrev_b32_e32 v206, 16, v91
	v_and_b32_e32 v207, 0xffff0000, v91
	v_pk_mul_f32 v[200:201], v[218:219], v[200:201] op_sel_hi:[0,1]
	v_pk_mul_f32 v[202:203], v[218:219], v[202:203] op_sel_hi:[0,1]
	v_pk_mul_f32 v[204:205], v[218:219], v[204:205] op_sel_hi:[0,1]
	v_pk_mul_f32 v[206:207], v[218:219], v[206:207] op_sel_hi:[0,1]
	v_pk_mul_f32 v[208:209], v[32:33], v[200:201]
	v_pk_mul_f32 v[210:211], v[34:35], v[202:203]
	v_pk_mul_f32 v[212:213], v[36:37], v[204:205]
	v_pk_mul_f32 v[214:215], v[38:39], v[206:207]
	global_store_dwordx4 v14, v[208:211], s[2:3]
	global_store_dwordx4 v14, v[212:215], s[2:3] offset:16
	s_waitcnt vmcnt(44)
	v_lshlrev_b32_e32 v200, 16, v92
	v_and_b32_e32 v201, 0xffff0000, v92
	v_lshlrev_b32_e32 v202, 16, v93
	v_and_b32_e32 v203, 0xffff0000, v93
	v_lshlrev_b32_e32 v204, 16, v94
	v_and_b32_e32 v205, 0xffff0000, v94
	v_lshlrev_b32_e32 v206, 16, v95
	v_and_b32_e32 v207, 0xffff0000, v95
	v_pk_mul_f32 v[200:201], v[218:219], v[200:201] op_sel_hi:[0,1]
	v_pk_mul_f32 v[202:203], v[218:219], v[202:203] op_sel_hi:[0,1]
	v_pk_mul_f32 v[204:205], v[218:219], v[204:205] op_sel_hi:[0,1]
	v_pk_mul_f32 v[206:207], v[218:219], v[206:207] op_sel_hi:[0,1]
	v_pk_mul_f32 v[224:225], v[40:41], v[200:201]
	v_pk_mul_f32 v[226:227], v[42:43], v[202:203]
	v_pk_mul_f32 v[228:229], v[44:45], v[204:205]
	v_pk_mul_f32 v[230:231], v[46:47], v[206:207]
	global_store_dwordx4 v15, v[224:227], s[2:3]
	global_store_dwordx4 v15, v[228:231], s[2:3] offset:16
	s_ashr_i32 s1, s0, 31
	s_lshl_b64 s[2:3], s[0:1], 13
	s_add_u32 s2, s7, s2
	s_addc_u32 s3, s6, s3
	s_add_i32 s0, s0, s80
	s_waitcnt vmcnt(45)
	v_fmamk_f32 v220, v50, 0x3a000000, v0
	v_mul_f32_e32 v221, 0x4b800000, v220
	v_cmp_gt_f32_e32 vcc, s4, v220
	s_nop 1
	v_cndmask_b32_e32 v220, v220, v221, vcc
	v_rsq_f32_e32 v218, v220
	s_nop 0
	v_mul_f32_e32 v221, 0x45800000, v218
	v_cndmask_b32_e32 v218, v218, v221, vcc
	s_waitcnt vmcnt(44)
	v_lshlrev_b32_e32 v200, 16, v96
	v_and_b32_e32 v201, 0xffff0000, v96
	v_lshlrev_b32_e32 v202, 16, v97
	v_and_b32_e32 v203, 0xffff0000, v97
	v_lshlrev_b32_e32 v204, 16, v98
	v_and_b32_e32 v205, 0xffff0000, v98
	v_lshlrev_b32_e32 v206, 16, v99
	v_and_b32_e32 v207, 0xffff0000, v99
	v_pk_mul_f32 v[200:201], v[218:219], v[200:201] op_sel_hi:[0,1]
	v_pk_mul_f32 v[202:203], v[218:219], v[202:203] op_sel_hi:[0,1]
	v_pk_mul_f32 v[204:205], v[218:219], v[204:205] op_sel_hi:[0,1]
	v_pk_mul_f32 v[206:207], v[218:219], v[206:207] op_sel_hi:[0,1]
	v_pk_mul_f32 v[208:209], v[16:17], v[200:201]
	v_pk_mul_f32 v[210:211], v[18:19], v[202:203]
	v_pk_mul_f32 v[212:213], v[20:21], v[204:205]
	v_pk_mul_f32 v[214:215], v[22:23], v[206:207]
	global_store_dwordx4 v12, v[208:211], s[2:3]
	global_store_dwordx4 v12, v[212:215], s[2:3] offset:16
	s_waitcnt vmcnt(45)
	v_lshlrev_b32_e32 v200, 16, v100
	v_and_b32_e32 v201, 0xffff0000, v100
	v_lshlrev_b32_e32 v202, 16, v101
	v_and_b32_e32 v203, 0xffff0000, v101
	v_lshlrev_b32_e32 v204, 16, v102
	v_and_b32_e32 v205, 0xffff0000, v102
	v_lshlrev_b32_e32 v206, 16, v103
	v_and_b32_e32 v207, 0xffff0000, v103
	v_pk_mul_f32 v[200:201], v[218:219], v[200:201] op_sel_hi:[0,1]
	v_pk_mul_f32 v[202:203], v[218:219], v[202:203] op_sel_hi:[0,1]
	v_pk_mul_f32 v[204:205], v[218:219], v[204:205] op_sel_hi:[0,1]
	v_pk_mul_f32 v[206:207], v[218:219], v[206:207] op_sel_hi:[0,1]
	v_pk_mul_f32 v[224:225], v[24:25], v[200:201]
	v_pk_mul_f32 v[226:227], v[26:27], v[202:203]
	v_pk_mul_f32 v[228:229], v[28:29], v[204:205]
	v_pk_mul_f32 v[230:231], v[30:31], v[206:207]
	global_store_dwordx4 v13, v[224:227], s[2:3]
	global_store_dwordx4 v13, v[228:231], s[2:3] offset:16
	s_waitcnt vmcnt(46)
	v_lshlrev_b32_e32 v200, 16, v104
	v_and_b32_e32 v201, 0xffff0000, v104
	v_lshlrev_b32_e32 v202, 16, v105
	v_and_b32_e32 v203, 0xffff0000, v105
	v_lshlrev_b32_e32 v204, 16, v106
	v_and_b32_e32 v205, 0xffff0000, v106
	v_lshlrev_b32_e32 v206, 16, v107
	v_and_b32_e32 v207, 0xffff0000, v107
	v_pk_mul_f32 v[200:201], v[218:219], v[200:201] op_sel_hi:[0,1]
	v_pk_mul_f32 v[202:203], v[218:219], v[202:203] op_sel_hi:[0,1]
	v_pk_mul_f32 v[204:205], v[218:219], v[204:205] op_sel_hi:[0,1]
	v_pk_mul_f32 v[206:207], v[218:219], v[206:207] op_sel_hi:[0,1]
	v_pk_mul_f32 v[208:209], v[32:33], v[200:201]
	v_pk_mul_f32 v[210:211], v[34:35], v[202:203]
	v_pk_mul_f32 v[212:213], v[36:37], v[204:205]
	v_pk_mul_f32 v[214:215], v[38:39], v[206:207]
	global_store_dwordx4 v14, v[208:211], s[2:3]
	global_store_dwordx4 v14, v[212:215], s[2:3] offset:16
	s_waitcnt vmcnt(47)
	v_lshlrev_b32_e32 v200, 16, v108
	v_and_b32_e32 v201, 0xffff0000, v108
	v_lshlrev_b32_e32 v202, 16, v109
	v_and_b32_e32 v203, 0xffff0000, v109
	v_lshlrev_b32_e32 v204, 16, v110
	v_and_b32_e32 v205, 0xffff0000, v110
	v_lshlrev_b32_e32 v206, 16, v111
	v_and_b32_e32 v207, 0xffff0000, v111
	v_pk_mul_f32 v[200:201], v[218:219], v[200:201] op_sel_hi:[0,1]
	v_pk_mul_f32 v[202:203], v[218:219], v[202:203] op_sel_hi:[0,1]
	v_pk_mul_f32 v[204:205], v[218:219], v[204:205] op_sel_hi:[0,1]
	v_pk_mul_f32 v[206:207], v[218:219], v[206:207] op_sel_hi:[0,1]
	v_pk_mul_f32 v[224:225], v[40:41], v[200:201]
	v_pk_mul_f32 v[226:227], v[42:43], v[202:203]
	v_pk_mul_f32 v[228:229], v[44:45], v[204:205]
	v_pk_mul_f32 v[230:231], v[46:47], v[206:207]
	global_store_dwordx4 v15, v[224:227], s[2:3]
	global_store_dwordx4 v15, v[228:231], s[2:3] offset:16
	s_ashr_i32 s1, s0, 31
	s_lshl_b64 s[2:3], s[0:1], 13
	s_add_u32 s2, s7, s2
	s_addc_u32 s3, s6, s3
	s_add_i32 s0, s0, s80
	s_waitcnt vmcnt(48)
; __device__ __forceinline__ void unpack8(u32x4 r, float* f) { f[0] = bflo(r.x); f[1] = bfhi(r.x); f[2] = bflo(r.y); f[3] = bfhi(r.y); f[4] = bflo(r.z); f[5] = bfhi(r.z); f[6] = bflo(r.w); f[7] = bfhi(r.w); }
; __device__ __forceinline__ void phase_final(const PT& p, int lane, int wave) {
;     ...
;         const float rs = rsqrtf(st2[m] * (1.f / 2048.f) + EPS);
;         const u32x4* xr = (const u32x4*)(X2 + (size_t)m * 2048) + lane; f32x4* orow = (f32x4*)(p.out + (size_t)m * 2048);
; #pragma unroll
;         for (int j = 0; j < 4; ++j) {
;             float f[8]; unpack8(xr[64 * j], f); const int c = 8 * (lane + 64 * j);
;             const f32x4 g0 = *(const f32x4*)(g + c), g1 = *(const f32x4*)(g + c + 4);
;             orow[(c >> 2)] = (f32x4){f[0] * rs * g0.x, f[1] * rs * g0.y, f[2] * rs * g0.z, f[3] * rs * g0.w};
;             orow[(c >> 2) + 1] = (f32x4){f[4] * rs * g1.x, f[5] * rs * g1.y, f[6] * rs * g1.z, f[7] * rs * g1.w};
	v_fmamk_f32 v220, v51, 0x3a000000, v0
	v_mul_f32_e32 v221, 0x4b800000, v220
	v_cmp_gt_f32_e32 vcc, s4, v220
	s_nop 1
	v_cndmask_b32_e32 v220, v220, v221, vcc
	v_rsq_f32_e32 v218, v220
	s_nop 0
	v_mul_f32_e32 v221, 0x45800000, v218
	v_cndmask_b32_e32 v218, v218, v221, vcc
	s_waitcnt vmcnt(47)
	v_lshlrev_b32_e32 v200, 16, v112
	v_and_b32_e32 v201, 0xffff0000, v112
	v_lshlrev_b32_e32 v202, 16, v113
	v_and_b32_e32 v203, 0xffff0000, v113
	v_lshlrev_b32_e32 v204, 16, v114
	v_and_b32_e32 v205, 0xffff0000, v114
	v_lshlrev_b32_e32 v206, 16, v115
	v_and_b32_e32 v207, 0xffff0000, v115
	v_pk_mul_f32 v[200:201], v[218:219], v[200:201] op_sel_hi:[0,1]
	v_pk_mul_f32 v[202:203], v[218:219], v[202:203] op_sel_hi:[0,1]
	v_pk_mul_f32 v[204:205], v[218:219], v[204:205] op_sel_hi:[0,1]
	v_pk_mul_f32 v[206:207], v[218:219], v[206:207] op_sel_hi:[0,1]
	v_pk_mul_f32 v[208:209], v[16:17], v[200:201]
	v_pk_mul_f32 v[210:211], v[18:19], v[202:203]
	v_pk_mul_f32 v[212:213], v[20:21], v[204:205]
	v_pk_mul_f32 v[214:215], v[22:23], v[206:207]
	global_store_dwordx4 v12, v[208:211], s[2:3]
	global_store_dwordx4 v12, v[212:215], s[2:3] offset:16
	s_waitcnt vmcnt(48)
	v_lshlrev_b32_e32 v200, 16, v116
	v_and_b32_e32 v201, 0xffff0000, v116
	v_lshlrev_b32_e32 v202, 16, v117
	v_and_b32_e32 v203, 0xffff0000, v117
	v_lshlrev_b32_e32 v204, 16, v118
	v_and_b32_e32 v205, 0xffff0000, v118
	v_lshlrev_b32_e32 v206, 16, v119
	v_and_b32_e32 v207, 0xffff0000, v119
	v_pk_mul_f32 v[200:201], v[218:219], v[200:201] op_sel_hi:[0,1]
	v_pk_mul_f32 v[202:203], v[218:219], v[202:203] op_sel_hi:[0,1]
	v_pk_mul_f32 v[204:205], v[218:219], v[204:205] op_sel_hi:[0,1]
	v_pk_mul_f32 v[206:207], v[218:219], v[206:207] op_sel_hi:[0,1]
	v_pk_mul_f32 v[224:225], v[24:25], v[200:201]
	v_pk_mul_f32 v[226:227], v[26:27], v[202:203]
	v_pk_mul_f32 v[228:229], v[28:29], v[204:205]
	v_pk_mul_f32 v[230:231], v[30:31], v[206:207]
	global_store_dwordx4 v13, v[224:227], s[2:3]
	global_store_dwordx4 v13, v[228:231], s[2:3] offset:16
	s_waitcnt vmcnt(49)
	v_lshlrev_b32_e32 v200, 16, v120
	v_and_b32_e32 v201, 0xffff0000, v120
	v_lshlrev_b32_e32 v202, 16, v121
	v_and_b32_e32 v203, 0xffff0000, v121
	v_lshlrev_b32_e32 v204, 16, v122
	v_and_b32_e32 v205, 0xffff0000, v122
	v_lshlrev_b32_e32 v206, 16, v123
	v_and_b32_e32 v207, 0xffff0000, v123
	v_pk_mul_f32 v[200:201], v[218:219], v[200:201] op_sel_hi:[0,1]
	v_pk_mul_f32 v[202:203], v[218:219], v[202:203] op_sel_hi:[0,1]
	v_pk_mul_f32 v[204:205], v[218:219], v[204:205] op_sel_hi:[0,1]
	v_pk_mul_f32 v[206:207], v[218:219], v[206:207] op_sel_hi:[0,1]
	v_pk_mul_f32 v[208:209], v[32:33], v[200:201]
	v_pk_mul_f32 v[210:211], v[34:35], v[202:203]
	v_pk_mul_f32 v[212:213], v[36:37], v[204:205]
	v_pk_mul_f32 v[214:215], v[38:39], v[206:207]
	global_store_dwordx4 v14, v[208:211], s[2:3]
	global_store_dwordx4 v14, v[212:215], s[2:3] offset:16
	s_waitcnt vmcnt(50)
	v_lshlrev_b32_e32 v200, 16, v124
	v_and_b32_e32 v201, 0xffff0000, v124
	v_lshlrev_b32_e32 v202, 16, v125
	v_and_b32_e32 v203, 0xffff0000, v125
	v_lshlrev_b32_e32 v204, 16, v126
	v_and_b32_e32 v205, 0xffff0000, v126
	v_lshlrev_b32_e32 v206, 16, v127
	v_and_b32_e32 v207, 0xffff0000, v127
	v_pk_mul_f32 v[200:201], v[218:219], v[200:201] op_sel_hi:[0,1]
	v_pk_mul_f32 v[202:203], v[218:219], v[202:203] op_sel_hi:[0,1]
	v_pk_mul_f32 v[204:205], v[218:219], v[204:205] op_sel_hi:[0,1]
	v_pk_mul_f32 v[206:207], v[218:219], v[206:207] op_sel_hi:[0,1]
	v_pk_mul_f32 v[224:225], v[40:41], v[200:201]
	v_pk_mul_f32 v[226:227], v[42:43], v[202:203]
	v_pk_mul_f32 v[228:229], v[44:45], v[204:205]
	v_pk_mul_f32 v[230:231], v[46:47], v[206:207]
	global_store_dwordx4 v15, v[224:227], s[2:3]
	global_store_dwordx4 v15, v[228:231], s[2:3] offset:16
	s_ashr_i32 s1, s0, 31
	s_lshl_b64 s[2:3], s[0:1], 13
	s_add_u32 s2, s7, s2
	s_addc_u32 s3, s6, s3
	s_add_i32 s0, s0, s80
	s_waitcnt vmcnt(51)
	v_fmamk_f32 v220, v52, 0x3a000000, v0
	v_mul_f32_e32 v221, 0x4b800000, v220
	v_cmp_gt_f32_e32 vcc, s4, v220
	s_nop 1
	v_cndmask_b32_e32 v220, v220, v221, vcc
	v_rsq_f32_e32 v218, v220
	s_nop 0
	v_mul_f32_e32 v221, 0x45800000, v218
	v_cndmask_b32_e32 v218, v218, v221, vcc
	s_waitcnt vmcnt(50)
	v_lshlrev_b32_e32 v200, 16, v128
	v_and_b32_e32 v201, 0xffff0000, v128
	v_lshlrev_b32_e32 v202, 16, v129
	v_and_b32_e32 v203, 0xffff0000, v129
	v_lshlrev_b32_e32 v204, 16, v130
	v_and_b32_e32 v205, 0xffff0000, v130
	v_lshlrev_b32_e32 v206, 16, v131
	v_and_b32_e32 v207, 0xffff0000, v131
	v_pk_mul_f32 v[200:201], v[218:219], v[200:201] op_sel_hi:[0,1]
	v_pk_mul_f32 v[202:203], v[218:219], v[202:203] op_sel_hi:[0,1]
	v_pk_mul_f32 v[204:205], v[218:219], v[204:205] op_sel_hi:[0,1]
	v_pk_mul_f32 v[206:207], v[218:219], v[206:207] op_sel_hi:[0,1]
	v_pk_mul_f32 v[208:209], v[16:17], v[200:201]
	v_pk_mul_f32 v[210:211], v[18:19], v[202:203]
	v_pk_mul_f32 v[212:213], v[20:21], v[204:205]
	v_pk_mul_f32 v[214:215], v[22:23], v[206:207]
	global_store_dwordx4 v12, v[208:211], s[2:3]
	global_store_dwordx4 v12, v[212:215], s[2:3] offset:16
	s_waitcnt vmcnt(51)
	v_lshlrev_b32_e32 v200, 16, v132
	v_and_b32_e32 v201, 0xffff0000, v132
	v_lshlrev_b32_e32 v202, 16, v133
	v_and_b32_e32 v203, 0xffff0000, v133
	v_lshlrev_b32_e32 v204, 16, v134
	v_and_b32_e32 v205, 0xffff0000, v134
	v_lshlrev_b32_e32 v206, 16, v135
	v_and_b32_e32 v207, 0xffff0000, v135
	v_pk_mul_f32 v[200:201], v[218:219], v[200:201] op_sel_hi:[0,1]
	v_pk_mul_f32 v[202:203], v[218:219], v[202:203] op_sel_hi:[0,1]
	v_pk_mul_f32 v[204:205], v[218:219], v[204:205] op_sel_hi:[0,1]
	v_pk_mul_f32 v[206:207], v[218:219], v[206:207] op_sel_hi:[0,1]
	v_pk_mul_f32 v[224:225], v[24:25], v[200:201]
	v_pk_mul_f32 v[226:227], v[26:27], v[202:203]
	v_pk_mul_f32 v[228:229], v[28:29], v[204:205]
	v_pk_mul_f32 v[230:231], v[30:31], v[206:207]
	global_store_dwordx4 v13, v[224:227], s[2:3]
	global_store_dwordx4 v13, v[228:231], s[2:3] offset:16
	s_waitcnt vmcnt(52)
; __device__ __forceinline__ void unpack8(u32x4 r, float* f) { f[0] = bflo(r.x); f[1] = bfhi(r.x); f[2] = bflo(r.y); f[3] = bfhi(r.y); f[4] = bflo(r.z); f[5] = bfhi(r.z); f[6] = bflo(r.w); f[7] = bfhi(r.w); }
; __device__ __forceinline__ void phase_final(const PT& p, int lane, int wave) {
;     ...
;         const float rs = rsqrtf(st2[m] * (1.f / 2048.f) + EPS);
;         const u32x4* xr = (const u32x4*)(X2 + (size_t)m * 2048) + lane; f32x4* orow = (f32x4*)(p.out + (size_t)m * 2048);
; #pragma unroll
;         for (int j = 0; j < 4; ++j) {
;             float f[8]; unpack8(xr[64 * j], f); const int c = 8 * (lane + 64 * j);
;             const f32x4 g0 = *(const f32x4*)(g + c), g1 = *(const f32x4*)(g + c + 4);
;             orow[(c >> 2)] = (f32x4){f[0] * rs * g0.x, f[1] * rs * g0.y, f[2] * rs * g0.z, f[3] * rs * g0.w};
;             orow[(c >> 2) + 1] = (f32x4){f[4] * rs * g1.x, f[5] * rs * g1.y, f[6] * rs * g1.z, f[7] * rs * g1.w};
	v_lshlrev_b32_e32 v200, 16, v136
	v_and_b32_e32 v201, 0xffff0000, v136
	v_lshlrev_b32_e32 v202, 16, v137
	v_and_b32_e32 v203, 0xffff0000, v137
	v_lshlrev_b32_e32 v204, 16, v138
	v_and_b32_e32 v205, 0xffff0000, v138
	v_lshlrev_b32_e32 v206, 16, v139
	v_and_b32_e32 v207, 0xffff0000, v139
	v_pk_mul_f32 v[200:201], v[218:219], v[200:201] op_sel_hi:[0,1]
	v_pk_mul_f32 v[202:203], v[218:219], v[202:203] op_sel_hi:[0,1]
	v_pk_mul_f32 v[204:205], v[218:219], v[204:205] op_sel_hi:[0,1]
	v_pk_mul_f32 v[206:207], v[218:219], v[206:207] op_sel_hi:[0,1]
	v_pk_mul_f32 v[208:209], v[32:33], v[200:201]
	v_pk_mul_f32 v[210:211], v[34:35], v[202:203]
	v_pk_mul_f32 v[212:213], v[36:37], v[204:205]
	v_pk_mul_f32 v[214:215], v[38:39], v[206:207]
	global_store_dwordx4 v14, v[208:211], s[2:3]
	global_store_dwordx4 v14, v[212:215], s[2:3] offset:16
	s_waitcnt vmcnt(53)
	v_lshlrev_b32_e32 v200, 16, v140
	v_and_b32_e32 v201, 0xffff0000, v140
	v_lshlrev_b32_e32 v202, 16, v141
	v_and_b32_e32 v203, 0xffff0000, v141
	v_lshlrev_b32_e32 v204, 16, v142
	v_and_b32_e32 v205, 0xffff0000, v142
	v_lshlrev_b32_e32 v206, 16, v143
	v_and_b32_e32 v207, 0xffff0000, v143
	v_pk_mul_f32 v[200:201], v[218:219], v[200:201] op_sel_hi:[0,1]
	v_pk_mul_f32 v[202:203], v[218:219], v[202:203] op_sel_hi:[0,1]
	v_pk_mul_f32 v[204:205], v[218:219], v[204:205] op_sel_hi:[0,1]
	v_pk_mul_f32 v[206:207], v[218:219], v[206:207] op_sel_hi:[0,1]
	v_pk_mul_f32 v[224:225], v[40:41], v[200:201]
	v_pk_mul_f32 v[226:227], v[42:43], v[202:203]
	v_pk_mul_f32 v[228:229], v[44:45], v[204:205]
	v_pk_mul_f32 v[230:231], v[46:47], v[206:207]
	global_store_dwordx4 v15, v[224:227], s[2:3]
	global_store_dwordx4 v15, v[228:231], s[2:3] offset:16
	s_ashr_i32 s1, s0, 31
	s_lshl_b64 s[2:3], s[0:1], 13
	s_add_u32 s2, s7, s2
	s_addc_u32 s3, s6, s3
	s_add_i32 s0, s0, s80
	s_waitcnt vmcnt(54)
	v_fmamk_f32 v220, v53, 0x3a000000, v0
	v_mul_f32_e32 v221, 0x4b800000, v220
	v_cmp_gt_f32_e32 vcc, s4, v220
	s_nop 1
	v_cndmask_b32_e32 v220, v220, v221, vcc
	v_rsq_f32_e32 v218, v220
	s_nop 0
	v_mul_f32_e32 v221, 0x45800000, v218
	v_cndmask_b32_e32 v218, v218, v221, vcc
	s_waitcnt vmcnt(53)
	v_lshlrev_b32_e32 v200, 16, v144
	v_and_b32_e32 v201, 0xffff0000, v144
	v_lshlrev_b32_e32 v202, 16, v145
	v_and_b32_e32 v203, 0xffff0000, v145
	v_lshlrev_b32_e32 v204, 16, v146
	v_and_b32_e32 v205, 0xffff0000, v146
	v_lshlrev_b32_e32 v206, 16, v147
	v_and_b32_e32 v207, 0xffff0000, v147
	v_pk_mul_f32 v[200:201], v[218:219], v[200:201] op_sel_hi:[0,1]
	v_pk_mul_f32 v[202:203], v[218:219], v[202:203] op_sel_hi:[0,1]
	v_pk_mul_f32 v[204:205], v[218:219], v[204:205] op_sel_hi:[0,1]
	v_pk_mul_f32 v[206:207], v[218:219], v[206:207] op_sel_hi:[0,1]
	v_pk_mul_f32 v[208:209], v[16:17], v[200:201]
	v_pk_mul_f32 v[210:211], v[18:19], v[202:203]
	v_pk_mul_f32 v[212:213], v[20:21], v[204:205]
	v_pk_mul_f32 v[214:215], v[22:23], v[206:207]
	global_store_dwordx4 v12, v[208:211], s[2:3]
	global_store_dwordx4 v12, v[212:215], s[2:3] offset:16
	s_waitcnt vmcnt(54)
	v_lshlrev_b32_e32 v200, 16, v148
	v_and_b32_e32 v201, 0xffff0000, v148
	v_lshlrev_b32_e32 v202, 16, v149
	v_and_b32_e32 v203, 0xffff0000, v149
	v_lshlrev_b32_e32 v204, 16, v150
	v_and_b32_e32 v205, 0xffff0000, v150
	v_lshlrev_b32_e32 v206, 16, v151
	v_and_b32_e32 v207, 0xffff0000, v151
	v_pk_mul_f32 v[200:201], v[218:219], v[200:201] op_sel_hi:[0,1]
	v_pk_mul_f32 v[202:203], v[218:219], v[202:203] op_sel_hi:[0,1]
	v_pk_mul_f32 v[204:205], v[218:219], v[204:205] op_sel_hi:[0,1]
	v_pk_mul_f32 v[206:207], v[218:219], v[206:207] op_sel_hi:[0,1]
	v_pk_mul_f32 v[224:225], v[24:25], v[200:201]
	v_pk_mul_f32 v[226:227], v[26:27], v[202:203]
	v_pk_mul_f32 v[228:229], v[28:29], v[204:205]
	v_pk_mul_f32 v[230:231], v[30:31], v[206:207]
	global_store_dwordx4 v13, v[224:227], s[2:3]
	global_store_dwordx4 v13, v[228:231], s[2:3] offset:16
	s_waitcnt vmcnt(55)
	v_lshlrev_b32_e32 v200, 16, v152
	v_and_b32_e32 v201, 0xffff0000, v152
	v_lshlrev_b32_e32 v202, 16, v153
	v_and_b32_e32 v203, 0xffff0000, v153
	v_lshlrev_b32_e32 v204, 16, v154
	v_and_b32_e32 v205, 0xffff0000, v154
	v_lshlrev_b32_e32 v206, 16, v155
	v_and_b32_e32 v207, 0xffff0000, v155
	v_pk_mul_f32 v[200:201], v[218:219], v[200:201] op_sel_hi:[0,1]
	v_pk_mul_f32 v[202:203], v[218:219], v[202:203] op_sel_hi:[0,1]
	v_pk_mul_f32 v[204:205], v[218:219], v[204:205] op_sel_hi:[0,1]
	v_pk_mul_f32 v[206:207], v[218:219], v[206:207] op_sel_hi:[0,1]
	v_pk_mul_f32 v[208:209], v[32:33], v[200:201]
	v_pk_mul_f32 v[210:211], v[34:35], v[202:203]
	v_pk_mul_f32 v[212:213], v[36:37], v[204:205]
	v_pk_mul_f32 v[214:215], v[38:39], v[206:207]
	global_store_dwordx4 v14, v[208:211], s[2:3]
	global_store_dwordx4 v14, v[212:215], s[2:3] offset:16
	s_waitcnt vmcnt(56)
	v_lshlrev_b32_e32 v200, 16, v156
	v_and_b32_e32 v201, 0xffff0000, v156
	v_lshlrev_b32_e32 v202, 16, v157
	v_and_b32_e32 v203, 0xffff0000, v157
	v_lshlrev_b32_e32 v204, 16, v158
	v_and_b32_e32 v205, 0xffff0000, v158
	v_lshlrev_b32_e32 v206, 16, v159
	v_and_b32_e32 v207, 0xffff0000, v159
	v_pk_mul_f32 v[200:201], v[218:219], v[200:201] op_sel_hi:[0,1]
	v_pk_mul_f32 v[202:203], v[218:219], v[202:203] op_sel_hi:[0,1]
	v_pk_mul_f32 v[204:205], v[218:219], v[204:205] op_sel_hi:[0,1]
	v_pk_mul_f32 v[206:207], v[218:219], v[206:207] op_sel_hi:[0,1]
	v_pk_mul_f32 v[224:225], v[40:41], v[200:201]
	v_pk_mul_f32 v[226:227], v[42:43], v[202:203]
	v_pk_mul_f32 v[228:229], v[44:45], v[204:205]
	v_pk_mul_f32 v[230:231], v[46:47], v[206:207]
	global_store_dwordx4 v15, v[224:227], s[2:3]
	global_store_dwordx4 v15, v[228:231], s[2:3] offset:16
	s_ashr_i32 s1, s0, 31
	s_lshl_b64 s[2:3], s[0:1], 13
	s_add_u32 s2, s7, s2
	s_addc_u32 s3, s6, s3
	s_add_i32 s0, s0, s80
	s_waitcnt vmcnt(57)
; __device__ __forceinline__ void unpack8(u32x4 r, float* f) { f[0] = bflo(r.x); f[1] = bfhi(r.x); f[2] = bflo(r.y); f[3] = bfhi(r.y); f[4] = bflo(r.z); f[5] = bfhi(r.z); f[6] = bflo(r.w); f[7] = bfhi(r.w); }
; __device__ __forceinline__ void phase_final(const PT& p, int lane, int wave) {
;     ...
;         const float rs = rsqrtf(st2[m] * (1.f / 2048.f) + EPS);
;         const u32x4* xr = (const u32x4*)(X2 + (size_t)m * 2048) + lane; f32x4* orow = (f32x4*)(p.out + (size_t)m * 2048);
; #pragma unroll
;         for (int j = 0; j < 4; ++j) {
;             float f[8]; unpack8(xr[64 * j], f); const int c = 8 * (lane + 64 * j);
;             const f32x4 g0 = *(const f32x4*)(g + c), g1 = *(const f32x4*)(g + c + 4);
;             orow[(c >> 2)] = (f32x4){f[0] * rs * g0.x, f[1] * rs * g0.y, f[2] * rs * g0.z, f[3] * rs * g0.w};
;             orow[(c >> 2) + 1] = (f32x4){f[4] * rs * g1.x, f[5] * rs * g1.y, f[6] * rs * g1.z, f[7] * rs * g1.w};
	v_fmamk_f32 v220, v54, 0x3a000000, v0
	v_mul_f32_e32 v221, 0x4b800000, v220
	v_cmp_gt_f32_e32 vcc, s4, v220
	s_nop 1
	v_cndmask_b32_e32 v220, v220, v221, vcc
	v_rsq_f32_e32 v218, v220
	s_nop 0
	v_mul_f32_e32 v221, 0x45800000, v218
	v_cndmask_b32_e32 v218, v218, v221, vcc
	s_waitcnt vmcnt(56)
	v_lshlrev_b32_e32 v200, 16, v160
	v_and_b32_e32 v201, 0xffff0000, v160
	v_lshlrev_b32_e32 v202, 16, v161
	v_and_b32_e32 v203, 0xffff0000, v161
	v_lshlrev_b32_e32 v204, 16, v162
	v_and_b32_e32 v205, 0xffff0000, v162
	v_lshlrev_b32_e32 v206, 16, v163
	v_and_b32_e32 v207, 0xffff0000, v163
	v_pk_mul_f32 v[200:201], v[218:219], v[200:201] op_sel_hi:[0,1]
	v_pk_mul_f32 v[202:203], v[218:219], v[202:203] op_sel_hi:[0,1]
	v_pk_mul_f32 v[204:205], v[218:219], v[204:205] op_sel_hi:[0,1]
	v_pk_mul_f32 v[206:207], v[218:219], v[206:207] op_sel_hi:[0,1]
	v_pk_mul_f32 v[208:209], v[16:17], v[200:201]
	v_pk_mul_f32 v[210:211], v[18:19], v[202:203]
	v_pk_mul_f32 v[212:213], v[20:21], v[204:205]
	v_pk_mul_f32 v[214:215], v[22:23], v[206:207]
	global_store_dwordx4 v12, v[208:211], s[2:3]
	global_store_dwordx4 v12, v[212:215], s[2:3] offset:16
	s_waitcnt vmcnt(57)
	v_lshlrev_b32_e32 v200, 16, v164
	v_and_b32_e32 v201, 0xffff0000, v164
	v_lshlrev_b32_e32 v202, 16, v165
	v_and_b32_e32 v203, 0xffff0000, v165
	v_lshlrev_b32_e32 v204, 16, v166
	v_and_b32_e32 v205, 0xffff0000, v166
	v_lshlrev_b32_e32 v206, 16, v167
	v_and_b32_e32 v207, 0xffff0000, v167
	v_pk_mul_f32 v[200:201], v[218:219], v[200:201] op_sel_hi:[0,1]
	v_pk_mul_f32 v[202:203], v[218:219], v[202:203] op_sel_hi:[0,1]
	v_pk_mul_f32 v[204:205], v[218:219], v[204:205] op_sel_hi:[0,1]
	v_pk_mul_f32 v[206:207], v[218:219], v[206:207] op_sel_hi:[0,1]
	v_pk_mul_f32 v[224:225], v[24:25], v[200:201]
	v_pk_mul_f32 v[226:227], v[26:27], v[202:203]
	v_pk_mul_f32 v[228:229], v[28:29], v[204:205]
	v_pk_mul_f32 v[230:231], v[30:31], v[206:207]
	global_store_dwordx4 v13, v[224:227], s[2:3]
	global_store_dwordx4 v13, v[228:231], s[2:3] offset:16
	s_waitcnt vmcnt(58)
	v_lshlrev_b32_e32 v200, 16, v168
	v_and_b32_e32 v201, 0xffff0000, v168
	v_lshlrev_b32_e32 v202, 16, v169
	v_and_b32_e32 v203, 0xffff0000, v169
	v_lshlrev_b32_e32 v204, 16, v170
	v_and_b32_e32 v205, 0xffff0000, v170
	v_lshlrev_b32_e32 v206, 16, v171
	v_and_b32_e32 v207, 0xffff0000, v171
	v_pk_mul_f32 v[200:201], v[218:219], v[200:201] op_sel_hi:[0,1]
	v_pk_mul_f32 v[202:203], v[218:219], v[202:203] op_sel_hi:[0,1]
	v_pk_mul_f32 v[204:205], v[218:219], v[204:205] op_sel_hi:[0,1]
	v_pk_mul_f32 v[206:207], v[218:219], v[206:207] op_sel_hi:[0,1]
	v_pk_mul_f32 v[208:209], v[32:33], v[200:201]
	v_pk_mul_f32 v[210:211], v[34:35], v[202:203]
	v_pk_mul_f32 v[212:213], v[36:37], v[204:205]
	v_pk_mul_f32 v[214:215], v[38:39], v[206:207]
	global_store_dwordx4 v14, v[208:211], s[2:3]
	global_store_dwordx4 v14, v[212:215], s[2:3] offset:16
	s_waitcnt vmcnt(59)
	v_lshlrev_b32_e32 v200, 16, v172
	v_and_b32_e32 v201, 0xffff0000, v172
	v_lshlrev_b32_e32 v202, 16, v173
	v_and_b32_e32 v203, 0xffff0000, v173
	v_lshlrev_b32_e32 v204, 16, v174
	v_and_b32_e32 v205, 0xffff0000, v174
	v_lshlrev_b32_e32 v206, 16, v175
	v_and_b32_e32 v207, 0xffff0000, v175
	v_pk_mul_f32 v[200:201], v[218:219], v[200:201] op_sel_hi:[0,1]
	v_pk_mul_f32 v[202:203], v[218:219], v[202:203] op_sel_hi:[0,1]
	v_pk_mul_f32 v[204:205], v[218:219], v[204:205] op_sel_hi:[0,1]
	v_pk_mul_f32 v[206:207], v[218:219], v[206:207] op_sel_hi:[0,1]
	v_pk_mul_f32 v[224:225], v[40:41], v[200:201]
	v_pk_mul_f32 v[226:227], v[42:43], v[202:203]
	v_pk_mul_f32 v[228:229], v[44:45], v[204:205]
	v_pk_mul_f32 v[230:231], v[46:47], v[206:207]
	global_store_dwordx4 v15, v[224:227], s[2:3]
	global_store_dwordx4 v15, v[228:231], s[2:3] offset:16
	s_ashr_i32 s1, s0, 31
	s_lshl_b64 s[2:3], s[0:1], 13
	s_add_u32 s2, s7, s2
	s_addc_u32 s3, s6, s3
	s_add_i32 s0, s0, s80
	s_waitcnt vmcnt(60)
; __device__ __forceinline__ void unpack8(u32x4 r, float* f) { f[0] = bflo(r.x); f[1] = bfhi(r.x); f[2] = bflo(r.y); f[3] = bfhi(r.y); f[4] = bflo(r.z); f[5] = bfhi(r.z); f[6] = bflo(r.w); f[7] = bfhi(r.w); }
; __device__ __forceinline__ void phase_final(const PT& p, int lane, int wave) {
;     ...
;         const float rs = rsqrtf(st2[m] * (1.f / 2048.f) + EPS);
;         const u32x4* xr = (const u32x4*)(X2 + (size_t)m * 2048) + lane; f32x4* orow = (f32x4*)(p.out + (size_t)m * 2048);
; #pragma unroll
;         for (int j = 0; j < 4; ++j) {
;             float f[8]; unpack8(xr[64 * j], f); const int c = 8 * (lane + 64 * j);
;             const f32x4 g0 = *(const f32x4*)(g + c), g1 = *(const f32x4*)(g + c + 4);
;             orow[(c >> 2)] = (f32x4){f[0] * rs * g0.x, f[1] * rs * g0.y, f[2] * rs * g0.z, f[3] * rs * g0.w};
;             orow[(c >> 2) + 1] = (f32x4){f[4] * rs * g1.x, f[5] * rs * g1.y, f[6] * rs * g1.z, f[7] * rs * g1.w};
	v_fmamk_f32 v220, v55, 0x3a000000, v0
	v_mul_f32_e32 v221, 0x4b800000, v220
	v_cmp_gt_f32_e32 vcc, s4, v220
	s_nop 1
	v_cndmask_b32_e32 v220, v220, v221, vcc
	v_rsq_f32_e32 v218, v220
	s_nop 0
	v_mul_f32_e32 v221, 0x45800000, v218
	v_cndmask_b32_e32 v218, v218, v221, vcc
	s_waitcnt vmcnt(59)
	v_lshlrev_b32_e32 v200, 16, v176
	v_and_b32_e32 v201, 0xffff0000, v176
	v_lshlrev_b32_e32 v202, 16, v177
	v_and_b32_e32 v203, 0xffff0000, v177
	v_lshlrev_b32_e32 v204, 16, v178
	v_and_b32_e32 v205, 0xffff0000, v178
	v_lshlrev_b32_e32 v206, 16, v179
	v_and_b32_e32 v207, 0xffff0000, v179
	v_pk_mul_f32 v[200:201], v[218:219], v[200:201] op_sel_hi:[0,1]
	v_pk_mul_f32 v[202:203], v[218:219], v[202:203] op_sel_hi:[0,1]
	v_pk_mul_f32 v[204:205], v[218:219], v[204:205] op_sel_hi:[0,1]
	v_pk_mul_f32 v[206:207], v[218:219], v[206:207] op_sel_hi:[0,1]
	v_pk_mul_f32 v[208:209], v[16:17], v[200:201]
	v_pk_mul_f32 v[210:211], v[18:19], v[202:203]
	v_pk_mul_f32 v[212:213], v[20:21], v[204:205]
	v_pk_mul_f32 v[214:215], v[22:23], v[206:207]
	global_store_dwordx4 v12, v[208:211], s[2:3]
	global_store_dwordx4 v12, v[212:215], s[2:3] offset:16
	s_waitcnt vmcnt(60)
	v_lshlrev_b32_e32 v200, 16, v180
	v_and_b32_e32 v201, 0xffff0000, v180
	v_lshlrev_b32_e32 v202, 16, v181
	v_and_b32_e32 v203, 0xffff0000, v181
	v_lshlrev_b32_e32 v204, 16, v182
	v_and_b32_e32 v205, 0xffff0000, v182
	v_lshlrev_b32_e32 v206, 16, v183
	v_and_b32_e32 v207, 0xffff0000, v183
	v_pk_mul_f32 v[200:201], v[218:219], v[200:201] op_sel_hi:[0,1]
	v_pk_mul_f32 v[202:203], v[218:219], v[202:203] op_sel_hi:[0,1]
	v_pk_mul_f32 v[204:205], v[218:219], v[204:205] op_sel_hi:[0,1]
	v_pk_mul_f32 v[206:207], v[218:219], v[206:207] op_sel_hi:[0,1]
	v_pk_mul_f32 v[224:225], v[24:25], v[200:201]
	v_pk_mul_f32 v[226:227], v[26:27], v[202:203]
	v_pk_mul_f32 v[228:229], v[28:29], v[204:205]
	v_pk_mul_f32 v[230:231], v[30:31], v[206:207]
	global_store_dwordx4 v13, v[224:227], s[2:3]
	global_store_dwordx4 v13, v[228:231], s[2:3] offset:16
	s_waitcnt vmcnt(61)
	v_lshlrev_b32_e32 v200, 16, v184
	v_and_b32_e32 v201, 0xffff0000, v184
	v_lshlrev_b32_e32 v202, 16, v185
	v_and_b32_e32 v203, 0xffff0000, v185
	v_lshlrev_b32_e32 v204, 16, v186
	v_and_b32_e32 v205, 0xffff0000, v186
	v_lshlrev_b32_e32 v206, 16, v187
	v_and_b32_e32 v207, 0xffff0000, v187
	v_pk_mul_f32 v[200:201], v[218:219], v[200:201] op_sel_hi:[0,1]
	v_pk_mul_f32 v[202:203], v[218:219], v[202:203] op_sel_hi:[0,1]
	v_pk_mul_f32 v[204:205], v[218:219], v[204:205] op_sel_hi:[0,1]
	v_pk_mul_f32 v[206:207], v[218:219], v[206:207] op_sel_hi:[0,1]
	v_pk_mul_f32 v[208:209], v[32:33], v[200:201]
	v_pk_mul_f32 v[210:211], v[34:35], v[202:203]
	v_pk_mul_f32 v[212:213], v[36:37], v[204:205]
	v_pk_mul_f32 v[214:215], v[38:39], v[206:207]
	global_store_dwordx4 v14, v[208:211], s[2:3]
	global_store_dwordx4 v14, v[212:215], s[2:3] offset:16
	s_waitcnt vmcnt(62)
	v_lshlrev_b32_e32 v200, 16, v188
	v_and_b32_e32 v201, 0xffff0000, v188
	v_lshlrev_b32_e32 v202, 16, v189
	v_and_b32_e32 v203, 0xffff0000, v189
	v_lshlrev_b32_e32 v204, 16, v190
	v_and_b32_e32 v205, 0xffff0000, v190
	v_lshlrev_b32_e32 v206, 16, v191
	v_and_b32_e32 v207, 0xffff0000, v191
	v_pk_mul_f32 v[200:201], v[218:219], v[200:201] op_sel_hi:[0,1]
	v_pk_mul_f32 v[202:203], v[218:219], v[202:203] op_sel_hi:[0,1]
	v_pk_mul_f32 v[204:205], v[218:219], v[204:205] op_sel_hi:[0,1]
	v_pk_mul_f32 v[206:207], v[218:219], v[206:207] op_sel_hi:[0,1]
	v_pk_mul_f32 v[224:225], v[40:41], v[200:201]
	v_pk_mul_f32 v[226:227], v[42:43], v[202:203]
	v_pk_mul_f32 v[228:229], v[44:45], v[204:205]
	v_pk_mul_f32 v[230:231], v[46:47], v[206:207]
	global_store_dwordx4 v15, v[224:227], s[2:3]
	global_store_dwordx4 v15, v[228:231], s[2:3] offset:16
